# prologue trimmed: adaLN layers 1-3 and most weight conversions deferred to idle workgroups of later GEMM phases; split-K deterministic adaLN; norm fast path
# speedup vs baseline: 1.0126x; 1.0095x over previous
.LBB0_893:
	s_cmpk_lt_i32 s67, 192
	s_cbranch_scc1 .Ladh_skip
	v_readlane_b32 s1, v254, 61
	s_mov_b32 s20, 0
	s_cmp_eq_u32 s1, 11
	s_cselect_b32 s20, 1, s20
	s_cmp_eq_u32 s1, 14
	s_cselect_b32 s20, 2, s20
	s_cmp_eq_u32 s1, 22
	s_cselect_b32 s20, 3, s20
	s_cmp_eq_u32 s20, 0
	s_cbranch_scc1 .Ladh_skip
	v_readlane_b32 s0, v254, 63
	s_sub_i32 s3, s67, 192
	s_load_dwordx4 s[8:11], s[60:61], 0x38
	s_load_dwordx4 s[12:15], s[60:61], 0x48
	v_mbcnt_lo_u32_b32 v0, -1, 0
	v_mbcnt_hi_u32_b32 v0, -1, v0
	s_lshl_b32 s16, s0, 14
	s_lshl_b32 s1, s0, 9
	v_lshl_add_u32 v18, v0, 2, s1
	v_lshl_add_u32 v19, v0, 4, s16
	s_waitcnt lgkmcnt(0)
	s_add_u32 s6, s8, 0x1000
	s_addc_u32 s7, s9, 0
	global_load_dword v26, v18, s[10:11]
	global_load_dword v27, v18, s[10:11] offset:256
	global_load_dword v28, v18, s[8:9]
	global_load_dword v29, v18, s[8:9] offset:256
	global_load_dword v30, v18, s[6:7]
	global_load_dword v31, v18, s[6:7] offset:256
	s_waitcnt vmcnt(0)
	v_mul_f32_e32 v74, 0xbfb8aa3b, v26
	v_mul_f32_e32 v75, 0xbfb8aa3b, v27
	v_mul_f32_e32 v76, 0xbfb8aa3b, v28
	v_mul_f32_e32 v77, 0xbfb8aa3b, v29
	v_mul_f32_e32 v78, 0xbfb8aa3b, v30
	v_mul_f32_e32 v79, 0xbfb8aa3b, v31
	v_exp_f32_e32 v74, v74
	v_exp_f32_e32 v75, v75
	v_exp_f32_e32 v76, v76
	v_exp_f32_e32 v77, v77
	v_exp_f32_e32 v78, v78
	v_exp_f32_e32 v79, v79
	v_add_f32_e32 v74, 1.0, v74
	v_add_f32_e32 v75, 1.0, v75
	v_add_f32_e32 v76, 1.0, v76
	v_add_f32_e32 v77, 1.0, v77
	v_add_f32_e32 v78, 1.0, v78
	v_add_f32_e32 v79, 1.0, v79
	v_rcp_f32_e32 v74, v74
	v_rcp_f32_e32 v75, v75
	v_rcp_f32_e32 v76, v76
	v_rcp_f32_e32 v77, v77
	v_rcp_f32_e32 v78, v78
	v_rcp_f32_e32 v79, v79
	v_mul_f32_e32 v26, v26, v74
	v_mul_f32_e32 v27, v27, v75
	v_mul_f32_e32 v28, v28, v76
	v_mul_f32_e32 v29, v29, v77
	v_mul_f32_e32 v30, v30, v78
	v_mul_f32_e32 v31, v31, v79
	v_mov_b32_e32 v90, v26
	v_mov_b32_e32 v91, v28
	v_mov_b32_e32 v92, v30
	v_mov_b32_e32 v93, 0
	v_mov_b32_e32 v94, v27
	v_mov_b32_e32 v95, v29
	v_mov_b32_e32 v96, v31
	v_mov_b32_e32 v97, 0
	ds_write_b128 v19, v[90:93]
	ds_write_b128 v19, v[94:97] offset:1024
	v_lshrrev_b32_e32 v20, 3, v0
	v_and_b32_e32 v21, 7, v0
	v_mul_u32_u24_e32 v22, 0x9000, v20
	v_lshl_add_u32 v22, v21, 4, v22
	s_mul_i32 s17, s0, 0x480000
	s_mul_i32 s1, s20, 0x2400000
	s_add_u32 s17, s17, s1
	s_add_u32 s12, s12, s17
	s_addc_u32 s13, s13, 0
	s_mul_i32 s1, s20, 0x9000
	s_add_u32 s14, s14, s1
	s_addc_u32 s15, s15, 0
	v_lshl_add_u32 v23, v20, 4, s16
	s_mul_i32 s17, s0, 0x180
	s_add_i32 s17, s17, 131072
	v_readlane_b32 s8, v255, 7
	v_readlane_b32 s9, v255, 8
	s_mul_i32 s1, s20, 0x1b000
	s_add_i32 s1, s1, 0x100000
	s_add_u32 s8, s8, s1
	s_addc_u32 s9, s9, 0
	s_mov_b32 s18, s3
	s_waitcnt lgkmcnt(0)
	v_lshl_add_u32 v94, v21, 4, s17
	s_mov_b32 s17, 131072
	v_lshl_add_u32 v95, v0, 2, s17
	v_lshlrev_b32_e32 v96, 2, v0
.Ladh_pass:
	s_lshl_b32 s19, s18, 7
	s_add_u32 s2, s12, s19
	s_addc_u32 s3, s13, 0
	v_mov_b32_e32 v2, 0
	v_mov_b32_e32 v3, 0
	v_mov_b32_e32 v4, 0
	v_mov_b32_e32 v5, 0
	v_mov_b32_e32 v6, 0
	v_mov_b32_e32 v7, 0
	v_mov_b32_e32 v8, 0
	v_mov_b32_e32 v9, 0
	v_mov_b32_e32 v10, 0
	v_mov_b32_e32 v11, 0
	v_mov_b32_e32 v12, 0
	v_mov_b32_e32 v13, 0
	global_load_dwordx4 v[26:29], v22, s[2:3] nt
	s_add_u32 s2, s2, 0x48000
	s_addc_u32 s3, s3, 0
	global_load_dwordx4 v[30:33], v22, s[2:3] nt
	s_add_u32 s2, s2, 0x48000
	s_addc_u32 s3, s3, 0
	global_load_dwordx4 v[34:37], v22, s[2:3] nt
	s_add_u32 s2, s2, 0x48000
	s_addc_u32 s3, s3, 0
	global_load_dwordx4 v[38:41], v22, s[2:3] nt
	s_add_u32 s2, s2, 0x48000
	s_addc_u32 s3, s3, 0
	global_load_dwordx4 v[42:45], v22, s[2:3] nt
	s_add_u32 s2, s2, 0x48000
	s_addc_u32 s3, s3, 0
	global_load_dwordx4 v[46:49], v22, s[2:3] nt
	s_add_u32 s2, s2, 0x48000
	s_addc_u32 s3, s3, 0
	global_load_dwordx4 v[50:53], v22, s[2:3] nt
	s_add_u32 s2, s2, 0x48000
	s_addc_u32 s3, s3, 0
	global_load_dwordx4 v[54:57], v22, s[2:3] nt
	s_add_u32 s2, s2, 0x48000
	s_addc_u32 s3, s3, 0
	global_load_dwordx4 v[58:61], v22, s[2:3] nt
	s_add_u32 s2, s2, 0x48000
	s_addc_u32 s3, s3, 0
	global_load_dwordx4 v[62:65], v22, s[2:3] nt
	s_add_u32 s2, s2, 0x48000
	s_addc_u32 s3, s3, 0
	global_load_dwordx4 v[66:69], v22, s[2:3] nt
	s_add_u32 s2, s2, 0x48000
	s_addc_u32 s3, s3, 0
	global_load_dwordx4 v[70:73], v22, s[2:3] nt
	s_add_u32 s2, s2, 0x48000
	s_addc_u32 s3, s3, 0
	global_load_dwordx4 v[74:77], v22, s[2:3] nt
	s_add_u32 s2, s2, 0x48000
	s_addc_u32 s3, s3, 0
	global_load_dwordx4 v[78:81], v22, s[2:3] nt
	s_add_u32 s2, s2, 0x48000
	s_addc_u32 s3, s3, 0
	global_load_dwordx4 v[82:85], v22, s[2:3] nt
	s_add_u32 s2, s2, 0x48000
	s_addc_u32 s3, s3, 0
	global_load_dwordx4 v[86:89], v22, s[2:3] nt
	s_add_u32 s2, s2, 0x48000
	s_addc_u32 s3, s3, 0
	ds_read_b128 v[14:17], v23
	ds_read_b128 v[90:93], v23 offset:128
	s_waitcnt vmcnt(15) lgkmcnt(1)
	v_fmac_f32_e32 v2, v26, v14
	v_fmac_f32_e32 v3, v27, v14
	v_fmac_f32_e32 v4, v28, v14
	v_fmac_f32_e32 v5, v29, v14
	v_fmac_f32_e32 v6, v26, v15
	v_fmac_f32_e32 v7, v27, v15
	v_fmac_f32_e32 v8, v28, v15
	v_fmac_f32_e32 v9, v29, v15
	v_fmac_f32_e32 v10, v26, v16
	v_fmac_f32_e32 v11, v27, v16
	v_fmac_f32_e32 v12, v28, v16
	v_fmac_f32_e32 v13, v29, v16
	ds_read_b128 v[14:17], v23 offset:256
	s_waitcnt vmcnt(14) lgkmcnt(1)
	v_fmac_f32_e32 v2, v30, v90
	v_fmac_f32_e32 v3, v31, v90
	v_fmac_f32_e32 v4, v32, v90
	v_fmac_f32_e32 v5, v33, v90
	v_fmac_f32_e32 v6, v30, v91
	v_fmac_f32_e32 v7, v31, v91
	v_fmac_f32_e32 v8, v32, v91
	v_fmac_f32_e32 v9, v33, v91
	v_fmac_f32_e32 v10, v30, v92
	v_fmac_f32_e32 v11, v31, v92
	v_fmac_f32_e32 v12, v32, v92
	v_fmac_f32_e32 v13, v33, v92
	ds_read_b128 v[90:93], v23 offset:384
	s_waitcnt vmcnt(13) lgkmcnt(1)
	v_fmac_f32_e32 v2, v34, v14
	v_fmac_f32_e32 v3, v35, v14
	v_fmac_f32_e32 v4, v36, v14
	v_fmac_f32_e32 v5, v37, v14
	v_fmac_f32_e32 v6, v34, v15
	v_fmac_f32_e32 v7, v35, v15
	v_fmac_f32_e32 v8, v36, v15
	v_fmac_f32_e32 v9, v37, v15
	v_fmac_f32_e32 v10, v34, v16
	v_fmac_f32_e32 v11, v35, v16
	v_fmac_f32_e32 v12, v36, v16
	v_fmac_f32_e32 v13, v37, v16
	ds_read_b128 v[14:17], v23 offset:512
	s_waitcnt vmcnt(12) lgkmcnt(1)
	v_fmac_f32_e32 v2, v38, v90
	v_fmac_f32_e32 v3, v39, v90
	v_fmac_f32_e32 v4, v40, v90
	v_fmac_f32_e32 v5, v41, v90
	v_fmac_f32_e32 v6, v38, v91
	v_fmac_f32_e32 v7, v39, v91
	v_fmac_f32_e32 v8, v40, v91
	v_fmac_f32_e32 v9, v41, v91
	v_fmac_f32_e32 v10, v38, v92
	v_fmac_f32_e32 v11, v39, v92
	v_fmac_f32_e32 v12, v40, v92
	v_fmac_f32_e32 v13, v41, v92
	ds_read_b128 v[90:93], v23 offset:640
	s_waitcnt vmcnt(11) lgkmcnt(1)
	v_fmac_f32_e32 v2, v42, v14
	v_fmac_f32_e32 v3, v43, v14
	v_fmac_f32_e32 v4, v44, v14
	v_fmac_f32_e32 v5, v45, v14
	v_fmac_f32_e32 v6, v42, v15
	v_fmac_f32_e32 v7, v43, v15
	v_fmac_f32_e32 v8, v44, v15
	v_fmac_f32_e32 v9, v45, v15
	v_fmac_f32_e32 v10, v42, v16
	v_fmac_f32_e32 v11, v43, v16
	v_fmac_f32_e32 v12, v44, v16
	v_fmac_f32_e32 v13, v45, v16
	ds_read_b128 v[14:17], v23 offset:768
	s_waitcnt vmcnt(10) lgkmcnt(1)
	v_fmac_f32_e32 v2, v46, v90
	v_fmac_f32_e32 v3, v47, v90
	v_fmac_f32_e32 v4, v48, v90
	v_fmac_f32_e32 v5, v49, v90
	v_fmac_f32_e32 v6, v46, v91
	v_fmac_f32_e32 v7, v47, v91
	v_fmac_f32_e32 v8, v48, v91
	v_fmac_f32_e32 v9, v49, v91
	v_fmac_f32_e32 v10, v46, v92
	v_fmac_f32_e32 v11, v47, v92
	v_fmac_f32_e32 v12, v48, v92
	v_fmac_f32_e32 v13, v49, v92
	ds_read_b128 v[90:93], v23 offset:896
	s_waitcnt vmcnt(9) lgkmcnt(1)
	v_fmac_f32_e32 v2, v50, v14
	v_fmac_f32_e32 v3, v51, v14
	v_fmac_f32_e32 v4, v52, v14
	v_fmac_f32_e32 v5, v53, v14
	v_fmac_f32_e32 v6, v50, v15
	v_fmac_f32_e32 v7, v51, v15
	v_fmac_f32_e32 v8, v52, v15
	v_fmac_f32_e32 v9, v53, v15
	v_fmac_f32_e32 v10, v50, v16
	v_fmac_f32_e32 v11, v51, v16
	v_fmac_f32_e32 v12, v52, v16
	v_fmac_f32_e32 v13, v53, v16
	ds_read_b128 v[14:17], v23 offset:1024
	s_waitcnt vmcnt(8) lgkmcnt(1)
	v_fmac_f32_e32 v2, v54, v90
	v_fmac_f32_e32 v3, v55, v90
	v_fmac_f32_e32 v4, v56, v90
	v_fmac_f32_e32 v5, v57, v90
	v_fmac_f32_e32 v6, v54, v91
	v_fmac_f32_e32 v7, v55, v91
	v_fmac_f32_e32 v8, v56, v91
	v_fmac_f32_e32 v9, v57, v91
	v_fmac_f32_e32 v10, v54, v92
	v_fmac_f32_e32 v11, v55, v92
	v_fmac_f32_e32 v12, v56, v92
	v_fmac_f32_e32 v13, v57, v92
	ds_read_b128 v[90:93], v23 offset:1152
	s_waitcnt vmcnt(7) lgkmcnt(1)
	v_fmac_f32_e32 v2, v58, v14
	v_fmac_f32_e32 v3, v59, v14
	v_fmac_f32_e32 v4, v60, v14
	v_fmac_f32_e32 v5, v61, v14
	v_fmac_f32_e32 v6, v58, v15
	v_fmac_f32_e32 v7, v59, v15
	v_fmac_f32_e32 v8, v60, v15
	v_fmac_f32_e32 v9, v61, v15
	v_fmac_f32_e32 v10, v58, v16
	v_fmac_f32_e32 v11, v59, v16
	v_fmac_f32_e32 v12, v60, v16
	v_fmac_f32_e32 v13, v61, v16
	ds_read_b128 v[14:17], v23 offset:1280
	s_waitcnt vmcnt(6) lgkmcnt(1)
	v_fmac_f32_e32 v2, v62, v90
	v_fmac_f32_e32 v3, v63, v90
	v_fmac_f32_e32 v4, v64, v90
	v_fmac_f32_e32 v5, v65, v90
	v_fmac_f32_e32 v6, v62, v91
	v_fmac_f32_e32 v7, v63, v91
	v_fmac_f32_e32 v8, v64, v91
	v_fmac_f32_e32 v9, v65, v91
	v_fmac_f32_e32 v10, v62, v92
	v_fmac_f32_e32 v11, v63, v92
	v_fmac_f32_e32 v12, v64, v92
	v_fmac_f32_e32 v13, v65, v92
	ds_read_b128 v[90:93], v23 offset:1408
	s_waitcnt vmcnt(5) lgkmcnt(1)
	v_fmac_f32_e32 v2, v66, v14
	v_fmac_f32_e32 v3, v67, v14
	v_fmac_f32_e32 v4, v68, v14
	v_fmac_f32_e32 v5, v69, v14
	v_fmac_f32_e32 v6, v66, v15
	v_fmac_f32_e32 v7, v67, v15
	v_fmac_f32_e32 v8, v68, v15
	v_fmac_f32_e32 v9, v69, v15
	v_fmac_f32_e32 v10, v66, v16
	v_fmac_f32_e32 v11, v67, v16
	v_fmac_f32_e32 v12, v68, v16
	v_fmac_f32_e32 v13, v69, v16
	ds_read_b128 v[14:17], v23 offset:1536
	s_waitcnt vmcnt(4) lgkmcnt(1)
	v_fmac_f32_e32 v2, v70, v90
	v_fmac_f32_e32 v3, v71, v90
	v_fmac_f32_e32 v4, v72, v90
	v_fmac_f32_e32 v5, v73, v90
	v_fmac_f32_e32 v6, v70, v91
	v_fmac_f32_e32 v7, v71, v91
	v_fmac_f32_e32 v8, v72, v91
	v_fmac_f32_e32 v9, v73, v91
	v_fmac_f32_e32 v10, v70, v92
	v_fmac_f32_e32 v11, v71, v92
	v_fmac_f32_e32 v12, v72, v92
	v_fmac_f32_e32 v13, v73, v92
	ds_read_b128 v[90:93], v23 offset:1664
	s_waitcnt vmcnt(3) lgkmcnt(1)
	v_fmac_f32_e32 v2, v74, v14
	v_fmac_f32_e32 v3, v75, v14
	v_fmac_f32_e32 v4, v76, v14
	v_fmac_f32_e32 v5, v77, v14
	v_fmac_f32_e32 v6, v74, v15
	v_fmac_f32_e32 v7, v75, v15
	v_fmac_f32_e32 v8, v76, v15
	v_fmac_f32_e32 v9, v77, v15
	v_fmac_f32_e32 v10, v74, v16
	v_fmac_f32_e32 v11, v75, v16
	v_fmac_f32_e32 v12, v76, v16
	v_fmac_f32_e32 v13, v77, v16
	ds_read_b128 v[14:17], v23 offset:1792
	s_waitcnt vmcnt(2) lgkmcnt(1)
	v_fmac_f32_e32 v2, v78, v90
	v_fmac_f32_e32 v3, v79, v90
	v_fmac_f32_e32 v4, v80, v90
	v_fmac_f32_e32 v5, v81, v90
	v_fmac_f32_e32 v6, v78, v91
	v_fmac_f32_e32 v7, v79, v91
	v_fmac_f32_e32 v8, v80, v91
	v_fmac_f32_e32 v9, v81, v91
	v_fmac_f32_e32 v10, v78, v92
	v_fmac_f32_e32 v11, v79, v92
	v_fmac_f32_e32 v12, v80, v92
	v_fmac_f32_e32 v13, v81, v92
	ds_read_b128 v[90:93], v23 offset:1920
	s_waitcnt vmcnt(1) lgkmcnt(1)
	v_fmac_f32_e32 v2, v82, v14
	v_fmac_f32_e32 v3, v83, v14
	v_fmac_f32_e32 v4, v84, v14
	v_fmac_f32_e32 v5, v85, v14
	v_fmac_f32_e32 v6, v82, v15
	v_fmac_f32_e32 v7, v83, v15
	v_fmac_f32_e32 v8, v84, v15
	v_fmac_f32_e32 v9, v85, v15
	v_fmac_f32_e32 v10, v82, v16
	v_fmac_f32_e32 v11, v83, v16
	v_fmac_f32_e32 v12, v84, v16
	v_fmac_f32_e32 v13, v85, v16
	s_waitcnt vmcnt(0) lgkmcnt(0)
	v_fmac_f32_e32 v2, v86, v90
	v_fmac_f32_e32 v3, v87, v90
	v_fmac_f32_e32 v4, v88, v90
	v_fmac_f32_e32 v5, v89, v90
	v_fmac_f32_e32 v6, v86, v91
	v_fmac_f32_e32 v7, v87, v91
	v_fmac_f32_e32 v8, v88, v91
	v_fmac_f32_e32 v9, v89, v91
	v_fmac_f32_e32 v10, v86, v92
	v_fmac_f32_e32 v11, v87, v92
	v_fmac_f32_e32 v12, v88, v92
	v_fmac_f32_e32 v13, v89, v92
	s_nop 1
	v_add_f32_dpp v2, v2, v2 row_ror:8 row_mask:0xf bank_mask:0xf
	v_add_f32_dpp v3, v3, v3 row_ror:8 row_mask:0xf bank_mask:0xf
	v_add_f32_dpp v4, v4, v4 row_ror:8 row_mask:0xf bank_mask:0xf
	v_add_f32_dpp v5, v5, v5 row_ror:8 row_mask:0xf bank_mask:0xf
	v_add_f32_dpp v6, v6, v6 row_ror:8 row_mask:0xf bank_mask:0xf
	v_add_f32_dpp v7, v7, v7 row_ror:8 row_mask:0xf bank_mask:0xf
	v_add_f32_dpp v8, v8, v8 row_ror:8 row_mask:0xf bank_mask:0xf
	v_add_f32_dpp v9, v9, v9 row_ror:8 row_mask:0xf bank_mask:0xf
	v_add_f32_dpp v10, v10, v10 row_ror:8 row_mask:0xf bank_mask:0xf
	v_add_f32_dpp v11, v11, v11 row_ror:8 row_mask:0xf bank_mask:0xf
	v_add_f32_dpp v12, v12, v12 row_ror:8 row_mask:0xf bank_mask:0xf
	v_add_f32_dpp v13, v13, v13 row_ror:8 row_mask:0xf bank_mask:0xf
	v_mov_b32_e32 v26, v2
	v_mov_b32_e32 v27, v3
	v_mov_b32_e32 v28, v4
	v_mov_b32_e32 v29, v5
	v_mov_b32_e32 v30, v6
	v_mov_b32_e32 v31, v7
	v_mov_b32_e32 v32, v8
	v_mov_b32_e32 v33, v9
	v_mov_b32_e32 v34, v10
	v_mov_b32_e32 v35, v11
	v_mov_b32_e32 v36, v12
	v_mov_b32_e32 v37, v13
	s_nop 1
	v_permlane16_swap_b32_e32 v26, v2
	v_permlane16_swap_b32_e32 v27, v3
	v_permlane16_swap_b32_e32 v28, v4
	v_permlane16_swap_b32_e32 v29, v5
	v_permlane16_swap_b32_e32 v30, v6
	v_permlane16_swap_b32_e32 v31, v7
	v_permlane16_swap_b32_e32 v32, v8
	v_permlane16_swap_b32_e32 v33, v9
	v_permlane16_swap_b32_e32 v34, v10
	v_permlane16_swap_b32_e32 v35, v11
	v_permlane16_swap_b32_e32 v36, v12
	v_permlane16_swap_b32_e32 v37, v13
	v_add_f32_e32 v2, v2, v26
	v_add_f32_e32 v3, v3, v27
	v_add_f32_e32 v4, v4, v28
	v_add_f32_e32 v5, v5, v29
	v_add_f32_e32 v6, v6, v30
	v_add_f32_e32 v7, v7, v31
	v_add_f32_e32 v8, v8, v32
	v_add_f32_e32 v9, v9, v33
	v_add_f32_e32 v10, v10, v34
	v_add_f32_e32 v11, v11, v35
	v_add_f32_e32 v12, v12, v36
	v_add_f32_e32 v13, v13, v37
	v_mov_b32_e32 v26, v2
	v_mov_b32_e32 v27, v3
	v_mov_b32_e32 v28, v4
	v_mov_b32_e32 v29, v5
	v_mov_b32_e32 v30, v6
	v_mov_b32_e32 v31, v7
	v_mov_b32_e32 v32, v8
	v_mov_b32_e32 v33, v9
	v_mov_b32_e32 v34, v10
	v_mov_b32_e32 v35, v11
	v_mov_b32_e32 v36, v12
	v_mov_b32_e32 v37, v13
	s_nop 1
	v_permlane32_swap_b32_e32 v26, v2
	v_permlane32_swap_b32_e32 v27, v3
	v_permlane32_swap_b32_e32 v28, v4
	v_permlane32_swap_b32_e32 v29, v5
	v_permlane32_swap_b32_e32 v30, v6
	v_permlane32_swap_b32_e32 v31, v7
	v_permlane32_swap_b32_e32 v32, v8
	v_permlane32_swap_b32_e32 v33, v9
	v_permlane32_swap_b32_e32 v34, v10
	v_permlane32_swap_b32_e32 v35, v11
	v_permlane32_swap_b32_e32 v36, v12
	v_permlane32_swap_b32_e32 v37, v13
	v_add_f32_e32 v2, v2, v26
	v_add_f32_e32 v3, v3, v27
	v_add_f32_e32 v4, v4, v28
	v_add_f32_e32 v5, v5, v29
	v_add_f32_e32 v6, v6, v30
	v_add_f32_e32 v7, v7, v31
	v_add_f32_e32 v8, v8, v32
	v_add_f32_e32 v9, v9, v33
	v_add_f32_e32 v10, v10, v34
	v_add_f32_e32 v11, v11, v35
	v_add_f32_e32 v12, v12, v36
	v_add_f32_e32 v13, v13, v37
	s_mov_b64 exec, 0xff
	ds_write_b128 v94, v[2:5]
	ds_write_b128 v94, v[6:9] offset:128
	ds_write_b128 v94, v[10:13] offset:256
	s_mov_b64 exec, -1
	s_waitcnt lgkmcnt(0)
	s_barrier
	s_cmp_lg_u32 s0, 0
	s_cbranch_scc1 .Ladh_join
	s_add_u32 s2, s14, s19
	s_addc_u32 s3, s15, 0
	s_mov_b32 exec_lo, -1
	s_mov_b32 exec_hi, 0
	global_load_dword v40, v96, s[2:3]
	ds_read_b32 v41, v95 offset:0
	ds_read_b32 v42, v95 offset:384
	ds_read_b32 v43, v95 offset:768
	ds_read_b32 v44, v95 offset:1152
	ds_read_b32 v45, v95 offset:1536
	ds_read_b32 v46, v95 offset:1920
	ds_read_b32 v47, v95 offset:2304
	ds_read_b32 v48, v95 offset:2688
	ds_read_b32 v49, v95 offset:128
	ds_read_b32 v50, v95 offset:512
	ds_read_b32 v51, v95 offset:896
	ds_read_b32 v52, v95 offset:1280
	ds_read_b32 v53, v95 offset:1664
	ds_read_b32 v54, v95 offset:2048
	ds_read_b32 v55, v95 offset:2432
	ds_read_b32 v56, v95 offset:2816
	ds_read_b32 v57, v95 offset:256
	ds_read_b32 v58, v95 offset:640
	ds_read_b32 v59, v95 offset:1024
	ds_read_b32 v60, v95 offset:1408
	ds_read_b32 v61, v95 offset:1792
	ds_read_b32 v62, v95 offset:2176
	ds_read_b32 v63, v95 offset:2560
	ds_read_b32 v64, v95 offset:2944
	s_waitcnt lgkmcnt(0)
	v_add_f32_e32 v41, v41, v42
	v_add_f32_e32 v41, v41, v43
	v_add_f32_e32 v41, v41, v44
	v_add_f32_e32 v41, v41, v45
	v_add_f32_e32 v41, v41, v46
	v_add_f32_e32 v41, v41, v47
	v_add_f32_e32 v41, v41, v48
	v_add_f32_e32 v49, v49, v50
	v_add_f32_e32 v49, v49, v51
	v_add_f32_e32 v49, v49, v52
	v_add_f32_e32 v49, v49, v53
	v_add_f32_e32 v49, v49, v54
	v_add_f32_e32 v49, v49, v55
	v_add_f32_e32 v49, v49, v56
	v_add_f32_e32 v57, v57, v58
	v_add_f32_e32 v57, v57, v59
	v_add_f32_e32 v57, v57, v60
	v_add_f32_e32 v57, v57, v61
	v_add_f32_e32 v57, v57, v62
	v_add_f32_e32 v57, v57, v63
	v_add_f32_e32 v57, v57, v64
	s_waitcnt vmcnt(0)
	v_add_f32_e32 v41, v41, v40
	v_add_f32_e32 v49, v49, v40
	v_add_f32_e32 v57, v57, v40
	s_add_u32 s2, s8, s19
	s_addc_u32 s3, s9, 0
	global_store_dword v96, v41, s[2:3]
	s_add_u32 s2, s2, 0x9000
	s_addc_u32 s3, s3, 0
	global_store_dword v96, v49, s[2:3]
	s_add_u32 s2, s2, 0x9000
	s_addc_u32 s3, s3, 0
	global_store_dword v96, v57, s[2:3]
	s_mov_b64 exec, -1
.Ladh_join:
	s_barrier
	s_add_i32 s18, s18, 64
	s_cmpk_lt_i32 s18, 0x120
	s_cbranch_scc1 .Ladh_pass

.LBB0_1013:
	s_andn2_b64 vcc, exec, s[2:3]
	s_cbranch_vccnz .LBB0_1130
	v_readlane_b32 s0, v255, 11
	s_cmp_lg_u32 s0, 0
	s_cbranch_scc1 .LBB0_1130
	v_mov_b32_e32 v0, v1
	s_lshl_b32 s0, s67, 3
	v_mbcnt_lo_u32_b32 v0, -1, v0
	s_waitcnt vmcnt(0)
	v_mbcnt_hi_u32_b32 v24, -1, v0
	v_readlane_b32 s1, v254, 63
	s_add_i32 s0, s0, s1
	s_waitcnt lgkmcnt(1)
	v_ashrrev_i32_e32 v3, 3, v24
	v_lshlrev_b32_e32 v25, 2, v24
	v_lshlrev_b32_e32 v0, 3, v24
	s_movk_i32 s1, 0x84
	s_cmpk_gt_i32 s0, 0xaff
	v_and_b32_e32 v2, 28, v25
	v_mul_lo_u32 v5, v3, s1
	v_add_u32_e32 v22, 8, v3
	v_add_u32_e32 v23, 16, v3
	v_add_u32_e32 v26, 24, v3
	v_and_b32_e32 v4, 56, v0
	v_lshlrev_b32_e32 v20, 2, v3
	v_and_b32_e32 v27, 15, v3
	s_cbranch_scc1 .LBB0_1026
	v_readlane_b32 s1, v254, 63
	v_readlane_b32 s8, v255, 5
	s_lshl_b32 s1, s1, 14
	v_readlane_b32 s10, v255, 7
	v_readlane_b32 s11, v255, 8
	s_add_i32 s1, s1, 0
	v_mul_u32_u24_e32 v0, 0x84, v4
	s_mov_b64 s[2:3], s[10:11]
	v_lshl_add_u32 v6, v2, 2, s1
	v_add3_u32 v7, s1, v0, v20
	v_readlane_b32 s9, v255, 6
	s_add_u32 s1, s2, 0x1a00000
	v_and_b32_e32 v8, 15, v22
	v_and_b32_e32 v9, 15, v26
	s_addc_u32 s8, s3, 0
	v_or_b32_e32 v10, 16, v27
	v_or_b32_e32 v11, 16, v8
	v_or_b32_e32 v12, 16, v9
	s_mov_b32 s9, s0
	s_branch .LBB0_1018
.LBB0_1017:
	s_add_i32 s9, s9, s92
	s_cmpk_lt_i32 s9, 0xb00
	s_cbranch_scc0 .LBB0_1026

.LBB0_1026:
	s_cmpk_gt_i32 s0, -1
	s_cbranch_scc1 .LBB0_1048
	v_readlane_b32 s2, v254, 63
	s_lshl_b32 s2, s2, 14
	v_readlane_b32 s8, v255, 5
	s_add_i32 s2, s2, 0
	v_mul_u32_u24_e32 v0, 0x84, v4
	v_readlane_b32 s10, v255, 7
	v_readlane_b32 s11, v255, 8
	v_add3_u32 v28, s2, v0, v20
	v_lshlrev_b32_e32 v0, 1, v4
	s_mov_b64 s[6:7], s[10:11]
	v_lshl_add_u32 v21, v2, 2, s2
	v_lshl_add_u64 v[10:11], s[6:7], 0, v[0:1]
	s_mov_b64 s[2:3], 0xa600000
	s_add_i32 s1, s0, 0x8400
	v_lshl_add_u64 v[6:7], v[10:11], 0, s[2:3]
	s_mov_b64 s[2:3], 0xa400000
	v_readlane_b32 s9, v255, 6
	v_lshl_add_u64 v[8:9], v[10:11], 0, s[2:3]
	s_mov_b64 s[2:3], 0x9e00000
	s_add_u32 s8, s6, 0x1a00000
	v_lshl_add_u64 v[10:11], v[10:11], 0, s[2:3]
	s_addc_u32 s9, s7, 0
	v_and_b32_e32 v29, 15, v22
	v_and_b32_e32 v30, 15, v26
	s_lshl_b32 s2, s1, 1
	v_or_b32_e32 v31, 16, v27
	s_waitcnt lgkmcnt(0)
	v_or_b32_e32 v32, 16, v29
	v_or_b32_e32 v33, 16, v30
	s_add_i32 s10, s2, 0xec00
	s_lshl_b32 s11, s92, 1
	s_lshl_b32 s12, s1, 5
	s_lshl_b32 s13, s92, 5
	s_branch .LBB0_1029

.LBB0_1048:
	s_cmpk_gt_i32 s0, -1
	s_cbranch_scc1 .LBB0_1094
	v_readlane_b32 s2, v254, 63
	s_lshl_b32 s2, s2, 14
	v_readlane_b32 s8, v255, 5
	s_add_i32 s2, s2, 0
	v_readlane_b32 s10, v255, 7
	v_readlane_b32 s11, v255, 8
	v_mul_u32_u24_e32 v0, 0x84, v4
	s_mov_b64 s[6:7], s[10:11]
	v_add3_u32 v29, s2, v0, v20
	v_lshlrev_b32_e32 v0, 1, v4
	v_lshl_add_u32 v28, v2, 2, s2
	v_lshl_add_u64 v[20:21], s[6:7], 0, v[0:1]
	s_mov_b64 s[2:3], 0xb600000
	v_lshl_add_u64 v[6:7], v[20:21], 0, s[2:3]
	s_mov_b64 s[2:3], 0xb000000
	v_lshl_add_u64 v[8:9], v[20:21], 0, s[2:3]
	s_mov_b64 s[2:3], 0xae00000
	v_lshl_add_u64 v[10:11], v[20:21], 0, s[2:3]
	s_mov_b64 s[2:3], 0xaa00000
	s_add_i32 s1, s0, 0x9e00
	v_lshl_add_u64 v[12:13], v[20:21], 0, s[2:3]
	s_mov_b64 s[2:3], 0xa800000
	v_readlane_b32 s9, v255, 6
	s_add_u32 s8, s6, 0x1600000
	v_lshl_add_u64 v[14:15], v[20:21], 0, s[2:3]
	s_mov_b64 s[2:3], 0xa600000
	s_addc_u32 s9, s7, 0
	v_lshl_add_u64 v[16:17], v[20:21], 0, s[2:3]
	s_mov_b64 s[2:3], 0xa400000
	v_lshl_add_u64 v[18:19], v[20:21], 0, s[2:3]
	s_mov_b64 s[2:3], 0x9e00000
	s_add_u32 s10, s6, 0x1a00000
	v_and_b32_e32 v30, 15, v22
	v_and_b32_e32 v31, 15, v26
	v_lshl_add_u64 v[20:21], v[20:21], 0, s[2:3]
	s_addc_u32 s11, s7, 0
	s_waitcnt lgkmcnt(0)
	v_or_b32_e32 v32, 16, v27
	v_or_b32_e32 v33, 16, v30
	v_or_b32_e32 v34, 16, v31
	s_lshl_b32 s12, s1, 1
	s_lshl_b32 s13, s92, 1
	s_lshl_b32 s14, s1, 5
	s_lshl_b32 s15, s92, 5
	s_branch .LBB0_1051

.LBB0_1094:
	v_readlane_b32 s0, v254, 63
	s_mov_b32 s20, 0
	s_load_dwordx4 s[8:11], s[60:61], 0x38
	s_load_dwordx4 s[12:15], s[60:61], 0x48
	v_mbcnt_lo_u32_b32 v0, -1, 0
	v_mbcnt_hi_u32_b32 v0, -1, v0
	s_lshl_b32 s16, s0, 14
	s_lshl_b32 s1, s0, 9
	v_lshl_add_u32 v18, v0, 2, s1
	v_lshl_add_u32 v19, v0, 4, s16
	s_waitcnt lgkmcnt(0)
	s_add_u32 s6, s8, 0x1000
	s_addc_u32 s7, s9, 0
	global_load_dword v26, v18, s[10:11]
	global_load_dword v27, v18, s[10:11] offset:256
	global_load_dword v28, v18, s[8:9]
	global_load_dword v29, v18, s[8:9] offset:256
	global_load_dword v30, v18, s[6:7]
	global_load_dword v31, v18, s[6:7] offset:256
	s_waitcnt vmcnt(0)
	v_mul_f32_e32 v74, 0xbfb8aa3b, v26
	v_mul_f32_e32 v75, 0xbfb8aa3b, v27
	v_mul_f32_e32 v76, 0xbfb8aa3b, v28
	v_mul_f32_e32 v77, 0xbfb8aa3b, v29
	v_mul_f32_e32 v78, 0xbfb8aa3b, v30
	v_mul_f32_e32 v79, 0xbfb8aa3b, v31
	v_exp_f32_e32 v74, v74
	v_exp_f32_e32 v75, v75
	v_exp_f32_e32 v76, v76
	v_exp_f32_e32 v77, v77
	v_exp_f32_e32 v78, v78
	v_exp_f32_e32 v79, v79
	v_add_f32_e32 v74, 1.0, v74
	v_add_f32_e32 v75, 1.0, v75
	v_add_f32_e32 v76, 1.0, v76
	v_add_f32_e32 v77, 1.0, v77
	v_add_f32_e32 v78, 1.0, v78
	v_add_f32_e32 v79, 1.0, v79
	v_rcp_f32_e32 v74, v74
	v_rcp_f32_e32 v75, v75
	v_rcp_f32_e32 v76, v76
	v_rcp_f32_e32 v77, v77
	v_rcp_f32_e32 v78, v78
	v_rcp_f32_e32 v79, v79
	v_mul_f32_e32 v26, v26, v74
	v_mul_f32_e32 v27, v27, v75
	v_mul_f32_e32 v28, v28, v76
	v_mul_f32_e32 v29, v29, v77
	v_mul_f32_e32 v30, v30, v78
	v_mul_f32_e32 v31, v31, v79
	v_mov_b32_e32 v90, v26
	v_mov_b32_e32 v91, v28
	v_mov_b32_e32 v92, v30
	v_mov_b32_e32 v93, 0
	v_mov_b32_e32 v94, v27
	v_mov_b32_e32 v95, v29
	v_mov_b32_e32 v96, v31
	v_mov_b32_e32 v97, 0
	ds_write_b128 v19, v[90:93]
	ds_write_b128 v19, v[94:97] offset:1024
	v_lshrrev_b32_e32 v20, 3, v0
	v_and_b32_e32 v21, 7, v0
	v_mul_u32_u24_e32 v22, 0x9000, v20
	v_lshl_add_u32 v22, v21, 4, v22
	s_mul_i32 s17, s0, 0x480000
	s_mul_i32 s1, s20, 0x2400000
	s_add_u32 s17, s17, s1
	s_add_u32 s12, s12, s17
	s_addc_u32 s13, s13, 0
	s_mul_i32 s1, s20, 0x9000
	s_add_u32 s14, s14, s1
	s_addc_u32 s15, s15, 0
	v_lshl_add_u32 v23, v20, 4, s16
	s_mul_i32 s17, s0, 0x180
	s_add_i32 s17, s17, 131072
	v_readlane_b32 s8, v255, 7
	v_readlane_b32 s9, v255, 8
	s_mul_i32 s1, s20, 0x1b000
	s_add_i32 s1, s1, 0x100000
	s_add_u32 s8, s8, s1
	s_addc_u32 s9, s9, 0
	s_mov_b32 s18, s67
	s_waitcnt lgkmcnt(0)
	v_lshl_add_u32 v94, v21, 4, s17
	s_mov_b32 s17, 131072
	v_lshl_add_u32 v95, v0, 2, s17
	v_lshlrev_b32_e32 v96, 2, v0

.Lads_join:
	s_barrier
	s_add_i32 s18, s18, 256
	s_cmpk_lt_i32 s18, 0x120
	s_cbranch_scc1 .Lads_pass

PROG:
	.byte	0, 0, 1
	.byte	1, 0, 1
	.byte	3, 0, 1
	.byte	4, 0, 1
	.byte	1, 1, 1
	.byte	5, 0, 1
	.byte	6, 0, 1
	.byte	7, 0, 1
	.byte	8, 0, 1
	.byte	1, 2, 1
	.byte	3, 1, 1
	.byte	4, 1, 1
	.byte	1, 4, 1
	.byte	3, 2, 1
	.byte	4, 2, 1
	.byte	2, 5, 1
	.byte	9, 0, 0
	.byte	10, 0, 1
	.byte	11, 0, 1
	.byte	8, 1, 1
	.byte	1, 6, 1
	.byte	3, 3, 1
	.byte	4, 3, 1
	.byte	1, 8, 1
	.byte	3, 4, 1
	.byte	4, 4, 1
	.byte	1, 9, 1
	.byte	12, 0, 1
	.byte	13, 0, 1
	.byte	14, 0, 1
	.byte	8, 2, 1
	.byte	1, 10, 1
	.byte	3, 5, 1
	.byte	4, 5, 1
	.byte	1, 12, 1
	.byte	3, 6, 1
	.byte	4, 6, 1
	.byte	1, 13, 1
	.byte	15, 0, 1
	.byte	16, 0, 1
	.byte	8, 3, 1
	.byte	1, 14, 1
	.byte	3, 7, 1
	.byte	4, 7, 1
	.byte	17, 0, 0
	.size	PROG, 135

	.protected	BGTAB
	.type	BGTAB,@object
	.globl	BGTAB
	.p2align	4, 0x0
BGTAB:
	.long	0, 0, 0, 0
	.long	0, 0, 0, 0
	.long	2816, 8448, 0, 0
	.long	8448, 12672, 33792, 36352
	.long	0, 0, 0, 0
	.long	0, 0, 0, 0
	.long	0, 0, 0, 0
	.long	0, 0, 0, 0
	.long	0, 0, 0, 0
	.long	0, 0, 0, 0
	.long	12672, 16896, 36352, 36864
	.long	16896, 21120, 40448, 40960
	.long	0, 0, 0, 0
	.long	21120, 25344, 36864, 38400
	.long	25344, 29568, 0, 0
	.long	0, 0, 0, 0
	.long	0, 0, 0, 0
	.long	0, 0, 0, 0
	.long	0, 0, 0, 0
	.long	0, 0, 0, 0
	.long	0, 0, 0, 0
	.long	29568, 33792, 38400, 40448
	.long	0, 0, 0, 0
	.long	0, 0, 0, 0
	.long	0, 0, 0, 0
	.long	0, 0, 0, 0
	.long	0, 0, 0, 0
	.long	0, 0, 0, 0
	.long	0, 0, 0, 0
	.long	0, 0, 0, 0
	.long	0, 0, 0, 0
	.long	0, 0, 0, 0
	.long	0, 0, 0, 0
	.long	0, 0, 0, 0
	.long	0, 0, 0, 0
	.long	0, 0, 0, 0
	.long	0, 0, 0, 0
	.long	0, 0, 0, 0
	.long	0, 0, 0, 0
	.long	0, 0, 0, 0
	.long	0, 0, 0, 0
	.long	0, 0, 0, 0
	.long	0, 0, 0, 0
	.long	0, 0, 0, 0
	.long	0, 0, 0, 0
	.size	BGTAB, 720

	.type	__hip_cuid_dfa6192372e94434,@object
